# grid barrier: two-level arrival (per blockIdx&7 group counter line, group leader -> global counter -> per-group release flag line) instead of gridDim atomics + gridDim pollers on one word; redundant c
# speedup vs baseline: 1.0518x; 1.0518x over previous
; #define TIDX get_tid_()
; DI void phase0(const Params& p, char* lds) {
;   if (blockIdx.x == 0 && TIDX < 64) { ((unsigned*)(p.ws + OFF_MISC))[TIDX] = 0u; ((unsigned*)(p.ws + OFF_MISC + 6144))[TIDX] = 0u; }
;   for (int it = blockIdx.x; it < 4; it += gridDim.x) {
;     const int l = it >> 1, kv = it & 1;
;     const float* pe = p.in[kv ? I_PEV : I_PEK] + (size_t)l * 2048;
;     const float* w = p.in[kv ? I_PV1 : I_PK1] + (size_t)l * 2048 * 256;
;     const int n = TIDX;
;     if (n < 256) {
;       float s = 0.f;
;       for (int k = 0; k < 2048; ++k) s += pe[k] * w[(size_t)k * 256 + n];
;       ((float*)(p.ws + OFF_MISC + 256))[it * 256 + n] = s;
;     }
;   }
.LBB0_772:
	v_readlane_b32 s4, v254, 1
	v_readlane_b32 s24, v254, 46
	v_readlane_b32 s25, v254, 47
	v_lshrrev_b32_e32 v0, 6, v129
	s_nop 3
	s_cmp_gt_u32 s4, 15
	s_cbranch_scc1 .LBB0_773
	v_readlane_b32 s22, v253, 5
	v_readlane_b32 s23, v253, 6
	v_lshlrev_b32_e32 v2, 7, v129
	v_cmp_gt_u32_e32 vcc, 9, v129
	s_and_saveexec_b64 s[8:9], vcc
	s_nop 4
	global_store_dword v2, v131, s[22:23] offset:256
	global_store_dword v2, v131, s[22:23] offset:-1792
	s_or_b64 exec, exec, s[8:9]
	v_readfirstlane_b32 s15, v0
	s_lshr_b32 s8, s4, 2
	s_and_b32 s26, s8, 1
	s_lshr_b32 s14, s8, 1
	s_lshl_b32 s9, s26, 3
	s_add_u32 s9, s9, 0x40
	s_load_dwordx2 s[22:23], s[24:25], s9
	s_lshl_b32 s9, s26, 4
	s_add_u32 s9, s9, 0x50
	s_load_dwordx2 s[10:11], s[24:25], s9
	s_lshl_b32 s54, s14, 13
	s_lshl_b32 s55, s15, 10
	s_add_u32 s54, s54, s55
	s_waitcnt lgkmcnt(0)
	s_add_u32 s22, s22, s54
	s_addc_u32 s23, s23, 0
	s_lshl_b32 s54, s14, 21
	s_lshl_b32 s55, s15, 18
	s_add_u32 s54, s54, s55
	s_and_b32 s55, s4, 3
	s_lshl_b32 s55, s55, 8
	s_add_u32 s54, s54, s55
	s_add_u32 s10, s10, s54
	s_addc_u32 s11, s11, 0
	v_and_b32_e32 v0, 63, v129
	v_lshlrev_b32_e32 v0, 2, v0
	v_mov_b32_e32 v1, 0
	s_mov_b32 s26, 8

; DI void grid_barrier(unsigned* ctr, unsigned target) {
;   __syncthreads();
;   if (threadIdx.x == 0) {
;     __threadfence();
;     __hip_atomic_fetch_add(ctr, 1u, __ATOMIC_RELAXED, __HIP_MEMORY_SCOPE_AGENT);
;     unsigned spins = 0;
;     while (__hip_atomic_load(ctr, __ATOMIC_RELAXED, __HIP_MEMORY_SCOPE_AGENT) < target && spins < (1u << 26)) { __builtin_amdgcn_s_sleep(2); ++spins; }
;     __threadfence();
;   }
;   __syncthreads();
; }
.LBB0_871:
	s_mov_b64 s[10:11], 0
	s_andn2_b64 vcc, exec, s[14:15]
	v_readlane_b32 s4, v254, 33
	s_cbranch_vccnz .LBB0_881
	v_readlane_b32 s4, v254, 33
	s_add_i32 s4, s4, 1
	s_waitcnt vmcnt(0) lgkmcnt(0)
	s_barrier
	s_mov_b64 s[8:9], exec
	v_readlane_b32 s10, v254, 36
	v_readlane_b32 s11, v254, 37
	s_and_b64 s[10:11], s[8:9], s[10:11]
	s_mov_b64 exec, s[10:11]
	s_cbranch_execz .LBB0_879
	buffer_wbl2 sc1
	v_readlane_b32 s24, v253, 5
	v_readlane_b32 s25, v253, 6
	v_readlane_b32 s10, v254, 1
	s_and_b32 s10, s10, 7
	s_sub_u32 s11, s33, s10
	s_add_u32 s11, s11, 7
	s_lshr_b32 s11, s11, 3
	s_mul_i32 s11, s11, s4
	s_lshl_b32 s10, s10, 7
	s_add_u32 s22, s24, s10
	s_addc_u32 s23, s25, 0
	s_add_u32 s14, s24, 0x500
	s_addc_u32 s15, s25, 0
	v_mov_b32_e32 v0, 1
	s_waitcnt vmcnt(0)
	global_atomic_add v1, v131, v0, s[22:23] offset:256 sc0
	s_waitcnt vmcnt(0)
	v_add_u32_e32 v1, 1, v1
	v_cmp_eq_u32_e32 vcc, s11, v1
	s_mov_b32 s10, 0
	s_cbranch_vccz .Lgb_wait
	global_atomic_add v131, v0, s[14:15]
	s_min_u32 s11, s33, 8
	s_mul_i32 s11, s11, s4
.Lgb_lp1:
	global_load_dword v1, v131, s[14:15] sc1
	s_add_u32 s10, s10, 1
	s_waitcnt vmcnt(0)
	v_cmp_gt_u32_e32 vcc, s11, v1
	s_cbranch_vccz .Lgb_rel
	s_cmp_lt_u32 s10, 0x400000
	s_cbranch_scc1 .Lgb_lp1
.Lgb_rel:
	global_atomic_add v131, v0, s[22:23] offset:-1792
	s_branch .Lgb_done
.Lgb_wait:
	global_load_dword v1, v131, s[22:23] offset:-1792 sc1
	s_add_u32 s10, s10, 1
	s_waitcnt vmcnt(0)
	v_cmp_gt_u32_e32 vcc, s4, v1
	s_cbranch_vccz .Lgb_done
	s_cmp_lt_u32 s10, 0x400000
	s_cbranch_scc1 .Lgb_wait
.Lgb_done:
	buffer_inv sc1
.LBB0_879:
	s_or_b64 exec, exec, s[8:9]
	s_mov_b64 s[10:11], -1
	s_barrier
